# up-projection sample-row split-K units: hand-scheduled K loop (all loads in flight) and earlier row-scale load, on top of v72
# baseline (speedup 1.0000x reference)
.LBB0_1155:
	s_and_b32 s8, s6, 0xc0
	s_and_b32 s9, s4, 0xffffffc0
	v_or_b32_e32 v1, s8, v76
	v_or_b32_e32 v0, s9, v76
	v_lshlrev_b32_e32 v192, 11, v1
	v_ashrrev_i32_e32 v1, 31, v0
	v_lshlrev_b64 v[4:5], 11, v[0:1]
	v_lshl_add_u64 v[116:117], v[74:75], 0, v[4:5]
	v_add_co_u32_e32 v118, vcc, 0x10000, v116
	v_lshl_add_u64 v[114:115], v[72:73], 0, v[192:193]
	s_nop 1
	v_addc_co_u32_e32 v119, vcc, 0, v117, vcc
	v_add_co_u32_e32 v120, vcc, 0x10000, v114
	s_nop 1
	v_addc_co_u32_e32 v121, vcc, 0, v115, vcc
	v_add_u32_e32 v89, 0x800, v77
	s_add_i32 s2, s2, s56
	s_add_i32 s4, s4, s5
	s_add_i32 s6, s6, s7
	s_cmpk_lt_i32 s2, 0x100
	global_load_dwordx4 v[92:95], v[114:115], off
	global_load_dwordx4 v[96:99], v[114:115], off offset:32
	global_load_dwordx4 v[100:103], v[120:121], off
	global_load_dwordx4 v[104:107], v[120:121], off offset:32
	global_load_dwordx4 v[108:111], v[116:117], off
	global_load_dwordx4 v[122:125], v[116:117], off offset:32
	global_load_dwordx4 v[126:129], v[118:119], off
	global_load_dwordx4 v[130:133], v[118:119], off offset:32
	global_load_dwordx4 v[134:137], v[114:115], off offset:64
	global_load_dwordx4 v[138:141], v[114:115], off offset:96
	global_load_dwordx4 v[142:145], v[120:121], off offset:64
	global_load_dwordx4 v[152:155], v[120:121], off offset:96
	global_load_dwordx4 v[156:159], v[116:117], off offset:64
	global_load_dwordx4 v[160:163], v[116:117], off offset:96
	global_load_dwordx4 v[164:167], v[118:119], off offset:64
	global_load_dwordx4 v[168:171], v[118:119], off offset:96
	global_load_dwordx4 v[172:175], v[114:115], off offset:128
	global_load_dwordx4 v[176:179], v[114:115], off offset:160
	global_load_dwordx4 v[180:183], v[120:121], off offset:128
	global_load_dwordx4 v[184:187], v[120:121], off offset:160
	global_load_dwordx4 v[188:191], v[116:117], off offset:128
	global_load_dwordx4 v[206:209], v[116:117], off offset:160
	global_load_dwordx4 v[210:213], v[118:119], off offset:128
	global_load_dwordx4 v[214:217], v[118:119], off offset:160
	s_waitcnt vmcnt(16)
	v_mfma_f32_32x32x16_bf16 v[32:47], v[92:95], v[108:111], 0
	v_mfma_f32_32x32x16_bf16 v[48:63], v[92:95], v[126:129], 0
	v_mfma_f32_32x32x16_bf16 v[0:15], v[100:103], v[108:111], 0
	v_mfma_f32_32x32x16_bf16 v[16:31], v[100:103], v[126:129], 0
	v_mfma_f32_32x32x16_bf16 v[32:47], v[96:99], v[122:125], v[32:47]
	v_mfma_f32_32x32x16_bf16 v[48:63], v[96:99], v[130:133], v[48:63]
	v_mfma_f32_32x32x16_bf16 v[0:15], v[104:107], v[122:125], v[0:15]
	v_mfma_f32_32x32x16_bf16 v[16:31], v[104:107], v[130:133], v[16:31]
	global_load_dwordx4 v[92:95], v[114:115], off offset:192
	global_load_dwordx4 v[96:99], v[114:115], off offset:224
	global_load_dwordx4 v[100:103], v[120:121], off offset:192
	global_load_dwordx4 v[104:107], v[120:121], off offset:224
	global_load_dwordx4 v[108:111], v[116:117], off offset:192
	global_load_dwordx4 v[122:125], v[116:117], off offset:224
	global_load_dwordx4 v[126:129], v[118:119], off offset:192
	global_load_dwordx4 v[130:133], v[118:119], off offset:224
	s_waitcnt vmcnt(16)
	v_mfma_f32_32x32x16_bf16 v[32:47], v[134:137], v[156:159], v[32:47]
	v_mfma_f32_32x32x16_bf16 v[48:63], v[134:137], v[164:167], v[48:63]
	v_mfma_f32_32x32x16_bf16 v[0:15], v[142:145], v[156:159], v[0:15]
	v_mfma_f32_32x32x16_bf16 v[16:31], v[142:145], v[164:167], v[16:31]
	v_mfma_f32_32x32x16_bf16 v[32:47], v[138:141], v[160:163], v[32:47]
	v_mfma_f32_32x32x16_bf16 v[48:63], v[138:141], v[168:171], v[48:63]
	v_mfma_f32_32x32x16_bf16 v[0:15], v[152:155], v[160:163], v[0:15]
	v_mfma_f32_32x32x16_bf16 v[16:31], v[152:155], v[168:171], v[16:31]
	s_waitcnt vmcnt(8)
	v_mfma_f32_32x32x16_bf16 v[32:47], v[172:175], v[188:191], v[32:47]
	v_mfma_f32_32x32x16_bf16 v[48:63], v[172:175], v[210:213], v[48:63]
	v_mfma_f32_32x32x16_bf16 v[0:15], v[180:183], v[188:191], v[0:15]
	v_mfma_f32_32x32x16_bf16 v[16:31], v[180:183], v[210:213], v[16:31]
	v_mfma_f32_32x32x16_bf16 v[32:47], v[176:179], v[206:209], v[32:47]
	v_mfma_f32_32x32x16_bf16 v[48:63], v[176:179], v[214:217], v[48:63]
	v_mfma_f32_32x32x16_bf16 v[0:15], v[184:187], v[206:209], v[0:15]
	v_mfma_f32_32x32x16_bf16 v[16:31], v[184:187], v[214:217], v[16:31]
	s_waitcnt vmcnt(0)
	v_mfma_f32_32x32x16_bf16 v[32:47], v[92:95], v[108:111], v[32:47]
	v_mfma_f32_32x32x16_bf16 v[48:63], v[92:95], v[126:129], v[48:63]
	v_mfma_f32_32x32x16_bf16 v[0:15], v[100:103], v[108:111], v[0:15]
	v_mfma_f32_32x32x16_bf16 v[16:31], v[100:103], v[126:129], v[16:31]
	v_mfma_f32_32x32x16_bf16 v[32:47], v[96:99], v[122:125], v[32:47]
	v_mfma_f32_32x32x16_bf16 v[48:63], v[96:99], v[130:133], v[48:63]
	v_mfma_f32_32x32x16_bf16 v[0:15], v[104:107], v[122:125], v[0:15]
	v_mfma_f32_32x32x16_bf16 v[16:31], v[104:107], v[130:133], v[16:31]
	s_nop 15
	v_add_u32_e32 v102, 0x1000, v77
	v_add_u32_e32 v103, 0x1800, v77
	v_add_u32_e32 v104, 0x2000, v77
	v_add_u32_e32 v105, 0x2800, v77
	v_add_u32_e32 v96, s8, v78
	v_ashrrev_i32_e32 v97, 31, v96
	v_or_b32_e32 v94, s9, v79
	v_ashrrev_i32_e32 v95, 31, v94
	v_add_u32_e32 v98, 0x3000, v77
	v_add_u32_e32 v99, 0x3800, v77
	v_lshl_add_u64 v[68:69], v[96:97], 2, s[30:31]
	v_lshlrev_b64 v[70:71], 13, v[96:97]
	v_lshl_add_u64 v[70:71], s[22:23], 0, v[70:71]
	v_lshl_add_u64 v[70:71], v[94:95], 1, v[70:71]
	global_load_dword v64, v[68:69], off
	ds_write2_b32 v77, v32, v48 offset1:32
	ds_write2_b32 v77, v33, v49 offset0:64 offset1:96
	ds_write2_b32 v77, v34, v50 offset0:128 offset1:160
	ds_write2_b32 v77, v35, v51 offset0:192 offset1:224
	ds_write2_b32 v89, v36, v52 offset1:32
	ds_write2_b32 v89, v37, v53 offset0:64 offset1:96
	ds_write2_b32 v89, v38, v54 offset0:128 offset1:160
	ds_write2_b32 v89, v39, v55 offset0:192 offset1:224
	ds_write2_b32 v102, v40, v56 offset1:32
	ds_write2_b32 v102, v41, v57 offset0:64 offset1:96
	ds_write2_b32 v102, v42, v58 offset0:128 offset1:160
	ds_write2_b32 v102, v43, v59 offset0:192 offset1:224
	ds_write2_b32 v103, v44, v60 offset1:32
	ds_write2_b32 v103, v45, v61 offset0:64 offset1:96
	ds_write2_b32 v103, v46, v62 offset0:128 offset1:160
	ds_write2_b32 v103, v47, v63 offset0:192 offset1:224
	ds_write2_b32 v104, v0, v16 offset1:32
	ds_write2_b32 v104, v1, v17 offset0:64 offset1:96
	ds_write2_b32 v104, v2, v18 offset0:128 offset1:160
	ds_write2_b32 v104, v3, v19 offset0:192 offset1:224
	ds_write2_b32 v105, v4, v20 offset1:32
	ds_write2_b32 v105, v5, v21 offset0:64 offset1:96
	ds_write2_b32 v105, v6, v22 offset0:128 offset1:160
	ds_write2_b32 v105, v7, v23 offset0:192 offset1:224
	ds_write2_b32 v98, v8, v24 offset1:32
	ds_write2_b32 v98, v9, v25 offset0:64 offset1:96
	ds_write2_b32 v98, v10, v26 offset0:128 offset1:160
	ds_write2_b32 v98, v11, v27 offset0:192 offset1:224
	ds_write2_b32 v99, v12, v28 offset1:32
	ds_write2_b32 v99, v13, v29 offset0:64 offset1:96
	ds_write2_b32 v99, v14, v30 offset0:128 offset1:160
	ds_write2_b32 v99, v15, v31 offset0:192 offset1:224
	s_waitcnt lgkmcnt(0)
	s_barrier
	ds_read_b128 v[0:3], v81
	ds_read_b128 v[4:7], v82
	ds_read_b128 v[8:11], v83
	ds_read_b128 v[12:15], v84
	ds_read_b128 v[16:19], v80
	ds_read_b128 v[20:23], v80 offset:16
	ds_read_b128 v[24:27], v85
	ds_read_b128 v[28:31], v86
	ds_read_b128 v[32:35], v87
	ds_read_b128 v[36:39], v88
	ds_read_b128 v[40:43], v80 offset:55312
	ds_read_b128 v[44:47], v80 offset:55296
	ds_read_b128 v[48:51], v80 offset:36880
	ds_read_b128 v[52:55], v80 offset:36864
	ds_read_b128 v[56:59], v80 offset:18448
	ds_read_b128 v[60:63], v80 offset:18432
	s_waitcnt lgkmcnt(10)
	v_add_f32_e32 v20, 0, v20
	v_add_f32_e32 v21, 0, v21
	v_add_f32_e32 v22, 0, v22
	s_waitcnt lgkmcnt(1)
	v_add_f32_e32 v20, v56, v20
	v_add_f32_e32 v21, v57, v21
	v_add_f32_e32 v20, v48, v20
	v_add_f32_e32 v21, v49, v21
	v_add_f32_e32 v20, v40, v20
	v_add_f32_e32 v21, v41, v21
	v_add_f32_e32 v12, v12, v20
	v_add_f32_e32 v13, v13, v21
	v_add_f32_e32 v8, v8, v12
	v_add_f32_e32 v9, v9, v13
	v_add_f32_e32 v4, v4, v8
	v_add_f32_e32 v5, v5, v9
	v_add_f32_e32 v0, v0, v4
	v_add_f32_e32 v23, 0, v23
	v_add_f32_e32 v16, 0, v16
	v_add_f32_e32 v17, 0, v17
	v_add_f32_e32 v22, v58, v22
	v_add_f32_e32 v1, v1, v5
	v_add_f32_e32 v18, 0, v18
	v_add_f32_e32 v23, v59, v23
	s_waitcnt lgkmcnt(0)
	v_add_f32_e32 v16, v60, v16
	v_add_f32_e32 v17, v61, v17
	v_add_f32_e32 v22, v50, v22
	v_add_f32_e32 v18, v62, v18
	v_add_f32_e32 v23, v51, v23
	v_add_f32_e32 v16, v52, v16
	v_add_f32_e32 v17, v53, v17
	v_add_f32_e32 v22, v42, v22
	v_add_f32_e32 v18, v54, v18
	v_add_f32_e32 v23, v43, v23
	v_add_f32_e32 v16, v44, v16
	v_add_f32_e32 v17, v45, v17
	v_add_f32_e32 v14, v14, v22
	v_add_f32_e32 v18, v46, v18
	v_add_f32_e32 v15, v15, v23
	v_add_f32_e32 v16, v36, v16
	v_add_f32_e32 v17, v37, v17
	v_add_f32_e32 v10, v10, v14
	v_add_f32_e32 v18, v38, v18
	v_add_f32_e32 v11, v11, v15
	v_add_f32_e32 v15, v32, v16
	v_add_f32_e32 v16, v33, v17
	v_add_f32_e32 v6, v6, v10
	v_add_f32_e32 v17, v34, v18
	v_add_f32_e32 v7, v7, v11
	v_add_f32_e32 v11, v28, v15
	v_add_f32_e32 v12, v29, v16
	v_add_f32_e32 v2, v2, v6
	v_add_f32_e32 v13, v30, v17
	v_add_f32_e32 v3, v3, v7
	v_add_f32_e32 v7, v24, v11
	v_add_f32_e32 v8, v25, v12
	v_add_f32_e32 v9, v26, v13
	v_add_f32_e32 v19, 0, v19
	v_add_f32_e32 v19, v63, v19
	v_add_f32_e32 v19, v55, v19
	v_add_f32_e32 v19, v47, v19
	v_add_f32_e32 v19, v39, v19
	v_add_f32_e32 v18, v35, v19
	v_add_f32_e32 v14, v31, v18
	v_add_f32_e32 v10, v27, v14
	s_waitcnt vmcnt(0)
	v_fmamk_f32 v4, v64, 0x3a800000, v235
	v_rsq_f32_e32 v4, v4
	s_nop 0
	v_mul_f32_e32 v3, v4, v3
	v_mul_f32_e32 v5, v4, v7
	v_mul_f32_e32 v6, v4, v8
	v_mul_f32_e32 v7, v4, v9
	v_mul_f32_e32 v8, v4, v10
	v_mul_f32_e32 v0, v4, v0
	v_mul_f32_e32 v9, v4, v1
	v_mul_f32_e32 v10, v4, v2
	v_max_f32_e32 v1, 0, v3
	v_max_f32_e32 v2, 0, v5
	v_max_f32_e32 v3, 0, v6
	v_max_f32_e32 v4, 0, v7
	v_max_f32_e32 v5, 0, v8
	v_max_f32_e32 v6, 0, v0
	v_max_f32_e32 v7, 0, v9
	v_max_f32_e32 v0, 0, v10
	v_pk_mul_f32 v[2:3], v[2:3], v[2:3]
	v_pk_mul_f32 v[4:5], v[4:5], v[4:5]
	v_pk_mul_f32 v[6:7], v[6:7], v[6:7]
	v_pk_mul_f32 v[8:9], v[0:1], v[0:1]
	v_cvt_pk_bf16_f32 v0, v2, v3
	v_cvt_pk_bf16_f32 v1, v4, v5
	v_cvt_pk_bf16_f32 v2, v6, v7
	v_cvt_pk_bf16_f32 v3, v8, v9
	global_store_dwordx4 v[70:71], v[0:3], off
	s_barrier
	s_cbranch_scc1 .LBB0_1155
